# strategy 2: attention output stores widened, 8 dwordx2 -> 4 dwordx4 per lane via v_permlane16_swap pairing of head-dim chunks (64-byte row segments instead of 32), on top of the fused P9
# baseline (speedup 1.0000x reference)
; __global__ void __launch_bounds__(NTHREADS, 2) fwd_megakernel(Args args) {
;     ...
;         for (int uid = u0; uid < u1; ++uid) {
;             const AttnUnit u = attn_decode(uid);
;             attn_commit(R, u.n, true, lds);
;             bf16x8 qf[4];
; #pragma unroll
;             for (int s4 = 0; s4 < 4; ++s4) qf[s4] = R.qf[s4];
;             asm volatile("s_waitcnt lgkmcnt(0)" ::: "memory"); __builtin_amdgcn_s_barrier(); asm volatile("" ::: "memory");
.LBB0_146:
	s_or_b64 exec, exec, s[60:61]
	s_waitcnt lgkmcnt(0)
	s_barrier
	s_waitcnt vmcnt(7)
	v_mov_b64_e32 v[62:63], v[34:35]
	s_waitcnt vmcnt(6)
	v_mov_b64_e32 v[58:59], v[38:39]
	s_waitcnt vmcnt(5)
	v_mov_b64_e32 v[54:55], v[42:43]
	s_waitcnt vmcnt(4)
	v_mov_b64_e32 v[50:51], v[46:47]
	s_and_b64 vcc, exec, s[58:59]
	v_mov_b64_e32 v[60:61], v[32:33]
	v_mov_b64_e32 v[56:57], v[36:37]
	v_mov_b64_e32 v[52:53], v[40:41]
	v_mov_b64_e32 v[48:49], v[44:45]
	s_mov_b32 s11, s75
	s_cbranch_vccnz .LBB0_153

; #define LAS __attribute__((address_space(3)))
; __device__ __forceinline__ void attn_compute(LAS unsigned char* lds, const bf16x8 (&qf)[4], const AttnUnit& u, bf16* og, float* lse) {
;     ...
; #pragma unroll
;     for (int kk = 0; kk < 5; ++kk) {
;         const int ks = ks0 + kk;
;         bf16x8 kf[2][4];
; #pragma unroll
;         for (int T = 0; T < 2; ++T)
; #pragma unroll
;             for (int s = 0; s < 4; ++s) kf[T][s] = *(const LAS bf16x8*)(Ks + (off_b(32 * ks + krow + 4 * T, 4 * s + kg) ^ par));
; #pragma unroll
;         for (int T = 0; T < 2; ++T) {
;             f32x4 a = {0.f, 0.f, 0.f, 0.f};
; #pragma unroll
;             for (int s = 0; s < 4; ++s) a = __builtin_amdgcn_mfma_f32_16x16x32_bf16(kf[T][s], qf[s], a, 0, 0, 0);
;             sc[kk][T] = a;
;         }
;     }
.LBB0_151:
	s_bfe_u32 s76, s11, 0x30005
	s_sub_i32 s11, 5, s8
	s_lshr_b32 s11, s63, s11
	s_cmp_eq_u32 s10, 1
	s_cselect_b32 s30, s33, s47
	s_cselect_b32 s31, s46, s64
	s_cmp_eq_u32 s10, 0
	v_readfirstlane_b32 s85, v178
	s_cselect_b32 s61, s91, s31
	s_cselect_b32 s60, s90, s30
	s_lshr_b32 s86, s85, 2
	s_and_b32 s83, s86, 0x3fffffe0
	s_not_b32 s30, s63
	v_or_b32_e32 v80, s83, v100
	s_lshl_b32 s30, s30, 15
	v_or_b32_e32 v64, v80, v101
	s_and_b32 s77, s30, 0x8000
	v_lshlrev_b32_e32 v72, 8, v64
	v_bitop3_b32 v64, v72, s77, v103 bitop3:0x36
	v_bitop3_b32 v65, v72, s77, v105 bitop3:0x36
	v_add_u32_e32 v64, 0, v64
	v_add_u32_e32 v68, 0, v65
	ds_read_b128 v[64:67], v64
	ds_read_b128 v[68:71], v68
	s_waitcnt lgkmcnt(1)
	v_mfma_f32_16x16x32_bf16 v[64:67], v[64:67], v[60:63], 0
	v_bitop3_b32 v73, v72, s77, v107 bitop3:0x36
	v_bitop3_b32 v72, v72, s77, v109 bitop3:0x36
	v_add_u32_e32 v73, 0, v73
	v_add_u32_e32 v76, 0, v72
	v_or_b32_e32 v80, 4, v80
	ds_read_b128 v[72:75], v73
	ds_read_b128 v[76:79], v76
	v_or_b32_e32 v83, v80, v101
	v_bfe_u32 v80, v80, 2, 2
	s_waitcnt lgkmcnt(2)
	v_mfma_f32_16x16x32_bf16 v[64:67], v[68:71], v[56:59], v[64:67]
	v_bitop3_b32 v85, v80, v99, v102 bitop3:0x36
	v_bitop3_b32 v86, v80, v104, v102 bitop3:0x36
	v_lshlrev_b32_e32 v83, 8, v83
	v_lshlrev_b32_e32 v85, 4, v85
	v_lshlrev_b32_e32 v86, 4, v86
	v_bitop3_b32 v85, v85, s77, v83 bitop3:0x36
	v_bitop3_b32 v86, v86, s77, v83 bitop3:0x36
	v_add_u32_e32 v85, 0, v85
	v_add_u32_e32 v68, 0, v86
	s_waitcnt lgkmcnt(1)
	v_mfma_f32_16x16x32_bf16 v[64:67], v[72:75], v[52:55], v[64:67]
	ds_read_b128 v[86:89], v85
	ds_read_b128 v[134:137], v68
	v_bitop3_b32 v68, v80, v106, v102 bitop3:0x36
	v_lshlrev_b32_e32 v68, 4, v68
	v_bitop3_b32 v72, v68, s77, v83 bitop3:0x36
	s_waitcnt lgkmcnt(2)
	v_mfma_f32_16x16x32_bf16 v[68:71], v[76:79], v[48:51], v[64:67]
	v_bitop3_b32 v76, v80, v108, v102 bitop3:0x36
	v_lshlrev_b32_e32 v76, 4, v76
	v_bitop3_b32 v76, v76, s77, v83 bitop3:0x36
	v_add_u32_e32 v64, 0, v72
	ds_read_b128 v[64:67], v64
	s_waitcnt lgkmcnt(2)
	v_mfma_f32_16x16x32_bf16 v[72:75], v[86:89], v[60:63], 0
	v_add_u32_e32 v76, 0, v76
	ds_read_b128 v[76:79], v76
	s_add_i32 s82, s83, 32
	s_waitcnt lgkmcnt(2)
	v_mfma_f32_16x16x32_bf16 v[72:75], v[134:137], v[56:59], v[72:75]
	v_or_b32_e32 v80, s82, v100
	s_add_i32 s80, s83, 64
	s_add_i32 s79, s83, 0x60
	s_waitcnt lgkmcnt(1)
	v_mfma_f32_16x16x32_bf16 v[64:67], v[64:67], v[52:55], v[72:75]
	s_add_i32 s78, s83, 0x80
	s_ashr_i32 s63, s62, 31
	s_and_b32 s54, s86, 0x3ffffff0
	v_or_b32_e32 v72, v80, v101
	v_lshlrev_b32_e32 v83, 8, v72
	v_bitop3_b32 v72, v83, s77, v103 bitop3:0x36
	v_bitop3_b32 v73, v83, s77, v105 bitop3:0x36
	s_waitcnt lgkmcnt(0)
	v_mfma_f32_16x16x32_bf16 v[64:67], v[76:79], v[48:51], v[64:67]
	v_add_u32_e32 v72, 0, v72
	v_add_u32_e32 v76, 0, v73
	ds_read_b128 v[72:75], v72
	ds_read_b128 v[76:79], v76
	s_waitcnt lgkmcnt(1)
	v_mfma_f32_16x16x32_bf16 v[72:75], v[72:75], v[60:63], 0
	v_bitop3_b32 v85, v83, s77, v107 bitop3:0x36
	v_bitop3_b32 v83, v83, s77, v109 bitop3:0x36
	v_add_u32_e32 v85, 0, v85
	v_add_u32_e32 v83, 0, v83
	v_or_b32_e32 v80, 4, v80
	ds_read_b128 v[86:89], v85
	ds_read_b128 v[134:137], v83
	v_or_b32_e32 v83, v80, v101
	v_bfe_u32 v80, v80, 2, 2
	s_waitcnt lgkmcnt(2)
	v_mfma_f32_16x16x32_bf16 v[72:75], v[76:79], v[56:59], v[72:75]
	v_bitop3_b32 v85, v80, v99, v102 bitop3:0x36
	v_bitop3_b32 v133, v80, v104, v102 bitop3:0x36
	v_lshlrev_b32_e32 v83, 8, v83
	v_lshlrev_b32_e32 v85, 4, v85
	v_lshlrev_b32_e32 v133, 4, v133
	v_bitop3_b32 v85, v85, s77, v83 bitop3:0x36
	v_bitop3_b32 v133, v133, s77, v83 bitop3:0x36
	v_add_u32_e32 v85, 0, v85
	v_add_u32_e32 v76, 0, v133
	s_waitcnt lgkmcnt(1)
	v_mfma_f32_16x16x32_bf16 v[72:75], v[86:89], v[52:55], v[72:75]
	ds_read_b128 v[138:141], v85
	ds_read_b128 v[142:145], v76
	v_bitop3_b32 v76, v80, v106, v102 bitop3:0x36
	v_lshlrev_b32_e32 v76, 4, v76
	v_bitop3_b32 v85, v76, s77, v83 bitop3:0x36
	s_waitcnt lgkmcnt(2)
	v_mfma_f32_16x16x32_bf16 v[76:79], v[134:137], v[48:51], v[72:75]
	v_bitop3_b32 v80, v80, v108, v102 bitop3:0x36
	v_lshlrev_b32_e32 v80, 4, v80
	v_bitop3_b32 v80, v80, s77, v83 bitop3:0x36
	v_add_u32_e32 v72, 0, v85
	ds_read_b128 v[72:75], v72
	s_waitcnt lgkmcnt(2)
	v_mfma_f32_16x16x32_bf16 v[86:89], v[138:141], v[60:63], 0
	v_add_u32_e32 v80, 0, v80
	ds_read_b128 v[134:137], v80
	v_or_b32_e32 v80, s80, v100
	s_waitcnt lgkmcnt(2)
	v_mfma_f32_16x16x32_bf16 v[86:89], v[142:145], v[56:59], v[86:89]
	v_or_b32_e32 v83, v80, v101
	v_lshlrev_b32_e32 v83, 8, v83
	v_bitop3_b32 v85, v83, s77, v103 bitop3:0x36
	s_waitcnt lgkmcnt(1)
	v_mfma_f32_16x16x32_bf16 v[72:75], v[72:75], v[52:55], v[86:89]
	v_add_u32_e32 v85, 0, v85
	v_or_b32_e32 v80, 4, v80
	s_lshl_b64 s[62:63], s[62:63], 12
	v_bitop3_b32 v86, v83, s77, v105 bitop3:0x36
	s_waitcnt lgkmcnt(0)
	v_mfma_f32_16x16x32_bf16 v[72:75], v[134:137], v[48:51], v[72:75]
	v_add_u32_e32 v133, 0, v86
	ds_read_b128 v[86:89], v85
	ds_read_b128 v[134:137], v133
	v_bitop3_b32 v85, v83, s77, v107 bitop3:0x36
	s_waitcnt lgkmcnt(1)
	v_mfma_f32_16x16x32_bf16 v[86:89], v[86:89], v[60:63], 0
	v_bitop3_b32 v83, v83, s77, v109 bitop3:0x36
	v_add_u32_e32 v85, 0, v85
	v_add_u32_e32 v83, 0, v83
	ds_read_b128 v[138:141], v85
	ds_read_b128 v[142:145], v83
	v_or_b32_e32 v83, v80, v101
	v_bfe_u32 v80, v80, 2, 2
	v_bitop3_b32 v85, v80, v99, v102 bitop3:0x36
	s_waitcnt lgkmcnt(2)
	v_mfma_f32_16x16x32_bf16 v[86:89], v[134:137], v[56:59], v[86:89]
	v_lshlrev_b32_e32 v83, 8, v83
	v_lshlrev_b32_e32 v85, 4, v85
	v_bitop3_b32 v133, v80, v104, v102 bitop3:0x36
	v_bitop3_b32 v85, v85, s77, v83 bitop3:0x36
	v_lshlrev_b32_e32 v133, 4, v133
	v_add_u32_e32 v85, 0, v85
	v_bitop3_b32 v133, v133, s77, v83 bitop3:0x36
	v_add_u32_e32 v133, 0, v133
	ds_read_b128 v[134:137], v85
	ds_read_b128 v[146:149], v133
	s_waitcnt lgkmcnt(3)
; #define LAS __attribute__((address_space(3)))
; __device__ __forceinline__ void attn_compute(LAS unsigned char* lds, const bf16x8 (&qf)[4], const AttnUnit& u, bf16* og, float* lse) {
;     ...
; #pragma unroll
;     for (int kk = 0; kk < 5; ++kk) {
;         const int ks = ks0 + kk;
;         bf16x8 kf[2][4];
; #pragma unroll
;         for (int T = 0; T < 2; ++T)
; #pragma unroll
;             for (int s = 0; s < 4; ++s) kf[T][s] = *(const LAS bf16x8*)(Ks + (off_b(32 * ks + krow + 4 * T, 4 * s + kg) ^ par));
; #pragma unroll
;         for (int T = 0; T < 2; ++T) {
;             f32x4 a = {0.f, 0.f, 0.f, 0.f};
; #pragma unroll
;             for (int s = 0; s < 4; ++s) a = __builtin_amdgcn_mfma_f32_16x16x32_bf16(kf[T][s], qf[s], a, 0, 0, 0);
;             sc[kk][T] = a;
;         }
;     }
;     float tb[5][2][4];
;     { const LAS float* tp = tab + (31 - 16 * (w & 1) - i15 + 8 * kg);
; #pragma unroll
;       for (int kk = 0; kk < 5; ++kk)
; #pragma unroll
;           for (int T = 0; T < 2; ++T)
; #pragma unroll
;               for (int jj = 0; jj < 4; ++jj) tb[kk][T][jj] = tp[32 * kk + 4 * T + jj]; }
	v_mfma_f32_16x16x32_bf16 v[86:89], v[138:141], v[52:55], v[86:89]
	v_bitop3_b32 v85, v80, v106, v102 bitop3:0x36
	v_lshlrev_b32_e32 v85, 4, v85
	v_bitop3_b32 v85, v85, s77, v83 bitop3:0x36
	v_add_u32_e32 v85, 0, v85
	s_waitcnt lgkmcnt(2)
	v_mfma_f32_16x16x32_bf16 v[138:141], v[142:145], v[48:51], v[86:89]
	v_bitop3_b32 v80, v80, v108, v102 bitop3:0x36
	v_lshlrev_b32_e32 v80, 4, v80
	v_bitop3_b32 v80, v80, s77, v83 bitop3:0x36
	ds_read_b128 v[86:89], v85
	s_waitcnt lgkmcnt(2)
	v_mfma_f32_16x16x32_bf16 v[134:137], v[134:137], v[60:63], 0
	v_add_u32_e32 v80, 0, v80
	ds_read_b128 v[142:145], v80
	v_or_b32_e32 v80, s79, v100
	s_waitcnt lgkmcnt(2)
	v_mfma_f32_16x16x32_bf16 v[134:137], v[146:149], v[56:59], v[134:137]
	v_or_b32_e32 v83, v80, v101
	v_lshlrev_b32_e32 v83, 8, v83
	v_bitop3_b32 v85, v83, s77, v103 bitop3:0x36
	s_waitcnt lgkmcnt(1)
	v_mfma_f32_16x16x32_bf16 v[86:89], v[86:89], v[52:55], v[134:137]
	v_add_u32_e32 v85, 0, v85
	v_or_b32_e32 v80, 4, v80
	s_andn2_b32 s30, 16, s86
	s_waitcnt lgkmcnt(0)
	v_mfma_f32_16x16x32_bf16 v[134:137], v[142:145], v[48:51], v[86:89]
	s_cmp_eq_u32 s84, 0
	s_nop 1
	v_bitop3_b32 v86, v83, s77, v105 bitop3:0x36
	v_add_u32_e32 v133, 0, v86
	ds_read_b128 v[86:89], v85
	ds_read_b128 v[142:145], v133
	s_waitcnt lgkmcnt(1)
	v_mfma_f32_16x16x32_bf16 v[86:89], v[86:89], v[60:63], 0
	v_bitop3_b32 v85, v83, s77, v107 bitop3:0x36
	v_bitop3_b32 v83, v83, s77, v109 bitop3:0x36
	v_add_u32_e32 v85, 0, v85
	v_add_u32_e32 v83, 0, v83
	ds_read_b128 v[146:149], v85
	ds_read_b128 v[150:153], v83
	v_or_b32_e32 v83, v80, v101
	v_bfe_u32 v80, v80, 2, 2
	v_bitop3_b32 v85, v80, v99, v102 bitop3:0x36
	s_waitcnt lgkmcnt(2)
	v_mfma_f32_16x16x32_bf16 v[86:89], v[142:145], v[56:59], v[86:89]
	v_lshlrev_b32_e32 v83, 8, v83
	v_lshlrev_b32_e32 v85, 4, v85
	v_bitop3_b32 v133, v80, v104, v102 bitop3:0x36
	v_bitop3_b32 v85, v85, s77, v83 bitop3:0x36
	v_lshlrev_b32_e32 v133, 4, v133
	v_add_u32_e32 v85, 0, v85
	v_bitop3_b32 v133, v133, s77, v83 bitop3:0x36
	v_add_u32_e32 v133, 0, v133
	ds_read_b128 v[142:145], v85
	ds_read_b128 v[154:157], v133
	s_waitcnt lgkmcnt(3)
	v_mfma_f32_16x16x32_bf16 v[86:89], v[146:149], v[52:55], v[86:89]
	v_bitop3_b32 v85, v80, v106, v102 bitop3:0x36
	v_lshlrev_b32_e32 v85, 4, v85
	v_bitop3_b32 v85, v85, s77, v83 bitop3:0x36
	v_add_u32_e32 v85, 0, v85
	s_waitcnt lgkmcnt(2)
	v_mfma_f32_16x16x32_bf16 v[146:149], v[150:153], v[48:51], v[86:89]
	v_bitop3_b32 v80, v80, v108, v102 bitop3:0x36
	v_lshlrev_b32_e32 v80, 4, v80
	v_bitop3_b32 v80, v80, s77, v83 bitop3:0x36
	ds_read_b128 v[86:89], v85
	s_waitcnt lgkmcnt(2)
	v_mfma_f32_16x16x32_bf16 v[142:145], v[142:145], v[60:63], 0
	v_add_u32_e32 v80, 0, v80
	ds_read_b128 v[150:153], v80
	v_or_b32_e32 v80, s78, v100
	s_waitcnt lgkmcnt(2)
	v_mfma_f32_16x16x32_bf16 v[142:145], v[154:157], v[56:59], v[142:145]
	v_or_b32_e32 v83, v80, v101
	v_lshlrev_b32_e32 v83, 8, v83
	v_bitop3_b32 v85, v83, s77, v103 bitop3:0x36
	s_waitcnt lgkmcnt(1)
	v_mfma_f32_16x16x32_bf16 v[86:89], v[86:89], v[52:55], v[142:145]
	v_add_u32_e32 v85, 0, v85
	v_or_b32_e32 v80, 4, v80
	s_waitcnt lgkmcnt(0)
	v_mfma_f32_16x16x32_bf16 v[142:145], v[150:153], v[48:51], v[86:89]
	s_nop 3
	v_bitop3_b32 v86, v83, s77, v105 bitop3:0x36
	v_add_u32_e32 v133, 0, v86
	ds_read_b128 v[86:89], v85
	ds_read_b128 v[150:153], v133
	s_waitcnt lgkmcnt(1)
	v_mfma_f32_16x16x32_bf16 v[86:89], v[86:89], v[60:63], 0
	v_bitop3_b32 v85, v83, s77, v107 bitop3:0x36
	v_bitop3_b32 v83, v83, s77, v109 bitop3:0x36
	v_add_u32_e32 v85, 0, v85
	v_add_u32_e32 v83, 0, v83
	ds_read_b128 v[154:157], v85
	ds_read_b128 v[158:161], v83
	v_or_b32_e32 v83, v80, v101
	v_bfe_u32 v80, v80, 2, 2
	v_bitop3_b32 v85, v80, v99, v102 bitop3:0x36
	s_waitcnt lgkmcnt(2)
	v_mfma_f32_16x16x32_bf16 v[86:89], v[150:153], v[56:59], v[86:89]
	v_lshlrev_b32_e32 v83, 8, v83
	v_lshlrev_b32_e32 v85, 4, v85
	v_bitop3_b32 v133, v80, v104, v102 bitop3:0x36
	v_bitop3_b32 v85, v85, s77, v83 bitop3:0x36
	v_lshlrev_b32_e32 v133, 4, v133
	v_add_u32_e32 v85, 0, v85
	v_bitop3_b32 v133, v133, s77, v83 bitop3:0x36
	v_add_u32_e32 v133, 0, v133
	ds_read_b128 v[150:153], v85
	ds_read_b128 v[162:165], v133
	s_waitcnt lgkmcnt(3)
	v_mfma_f32_16x16x32_bf16 v[86:89], v[154:157], v[52:55], v[86:89]
	v_bitop3_b32 v85, v80, v106, v102 bitop3:0x36
	v_lshlrev_b32_e32 v85, 4, v85
	v_bitop3_b32 v85, v85, s77, v83 bitop3:0x36
	v_add_u32_e32 v85, 0, v85
	s_waitcnt lgkmcnt(2)
	v_mfma_f32_16x16x32_bf16 v[154:157], v[158:161], v[48:51], v[86:89]
	v_bitop3_b32 v80, v80, v108, v102 bitop3:0x36
	v_lshlrev_b32_e32 v80, 4, v80
	v_bitop3_b32 v80, v80, s77, v83 bitop3:0x36
	ds_read_b128 v[86:89], v85
	s_waitcnt lgkmcnt(2)
	v_mfma_f32_16x16x32_bf16 v[60:63], v[150:153], v[60:63], 0
	v_add_u32_e32 v80, 0, v80
	s_waitcnt lgkmcnt(1)
	v_mfma_f32_16x16x32_bf16 v[56:59], v[162:165], v[56:59], v[60:63]
	s_nop 4
	ds_read_b128 v[60:63], v80
	s_waitcnt lgkmcnt(1)
	v_mfma_f32_16x16x32_bf16 v[52:55], v[86:89], v[52:55], v[56:59]
	s_waitcnt lgkmcnt(0)
	v_mfma_f32_16x16x32_bf16 v[52:55], v[60:63], v[48:51], v[52:55]
	v_sub_u32_e32 v48, s30, v92
	v_lshl_add_u32 v48, v48, 2, v110
	s_cselect_b64 s[30:31], -1, 0
	s_cmpk_lt_u32 s85, 0x200
	ds_read2_b32 v[56:57], v48 offset0:15 offset1:16
	ds_read2_b32 v[58:59], v48 offset0:17 offset1:18
	ds_read2_b32 v[60:61], v48 offset0:19 offset1:20
	ds_read2_b32 v[62:63], v48 offset0:21 offset1:22
	ds_read2_b32 v[150:151], v48 offset0:47 offset1:48
	ds_read2_b32 v[152:153], v48 offset0:49 offset1:50
	ds_read2_b32 v[158:159], v48 offset0:51 offset1:52
	ds_read2_b32 v[160:161], v48 offset0:53 offset1:54
	ds_read2_b32 v[162:163], v48 offset0:79 offset1:80
	ds_read2_b32 v[164:165], v48 offset0:81 offset1:82
	ds_read2_b32 v[166:167], v48 offset0:83 offset1:84
	ds_read2_b32 v[168:169], v48 offset0:85 offset1:86
	ds_read2_b32 v[170:171], v48 offset0:111 offset1:112
	ds_read2_b32 v[172:173], v48 offset0:113 offset1:114
	ds_read2_b32 v[174:175], v48 offset0:115 offset1:116
	ds_read2_b32 v[176:177], v48 offset0:117 offset1:118
	ds_read2_b32 v[88:89], v48 offset0:143 offset1:144
	ds_read2_b32 v[86:87], v48 offset0:145 offset1:146
	ds_read2_b32 v[50:51], v48 offset0:147 offset1:148
	ds_read2_b32 v[48:49], v48 offset0:149 offset1:150
	s_cselect_b64 s[86:87], -1, 0
	s_waitcnt lgkmcnt(14)
; __device__ __forceinline__ void attn_compute(LAS unsigned char* lds, const bf16x8 (&qf)[4], const AttnUnit& u, bf16* og, float* lse) {
;     ...
;     const float SCL = 0.08838834764831845f * 1.4426950408889634f;
;     float mx = -1e30f;
; #pragma unroll
;     for (int kk = 0; kk < 5; ++kk) {
;         const bool dead = (n == 0) && (ks0 + kk < 4);
; #pragma unroll
;         for (int T = 0; T < 2; ++T)
; #pragma unroll
;             for (int jj = 0; jj < 4; ++jj) { float v = sc[kk][T][jj] * SCL + tb[kk][T][jj]; v = dead ? -1e30f : v; sc[kk][T][jj] = v; mx = fmaxf(mx, v); }
;     }
;     mx = fmaxf(mx, __shfl_xor(mx, 16)); mx = fmaxf(mx, __shfl_xor(mx, 32));
	v_fmamk_f32 v56, v68, 0x3e0293ee, v56
	s_and_b64 vcc, s[30:31], s[86:87]
	v_fmac_f32_e32 v57, 0x3e0293ee, v69
	v_cndmask_b32_e32 v56, v56, v131, vcc
	v_cndmask_b32_e32 v57, v57, v131, vcc
	v_fmamk_f32 v58, v70, 0x3e0293ee, v58
	v_fmac_f32_e32 v59, 0x3e0293ee, v71
	v_max3_f32 v68, v56, s74, v57
	v_cndmask_b32_e32 v58, v58, v131, vcc
	v_cndmask_b32_e32 v59, v59, v131, vcc
	v_fmamk_f32 v60, v64, 0x3e0293ee, v60
	v_fmac_f32_e32 v61, 0x3e0293ee, v65
	s_cmpk_lt_u32 s85, 0x180
	v_max3_f32 v68, v68, v58, v59
	v_cndmask_b32_e32 v60, v60, v131, vcc
	v_cndmask_b32_e32 v61, v61, v131, vcc
	v_fmamk_f32 v62, v66, 0x3e0293ee, v62
	v_fmac_f32_e32 v63, 0x3e0293ee, v67
	s_cselect_b64 s[86:87], -1, 0
	v_max3_f32 v64, v68, v60, v61
	v_cndmask_b32_e32 v62, v62, v131, vcc
	v_cndmask_b32_e32 v63, v63, v131, vcc
	v_fmamk_f32 v65, v76, 0x3e0293ee, v150
	s_and_b64 vcc, s[30:31], s[86:87]
	v_fmac_f32_e32 v151, 0x3e0293ee, v77
	v_max3_f32 v64, v64, v62, v63
	v_cndmask_b32_e32 v69, v65, v131, vcc
	v_cndmask_b32_e32 v70, v151, v131, vcc
	v_fmamk_f32 v65, v78, 0x3e0293ee, v152
	v_fmac_f32_e32 v153, 0x3e0293ee, v79
	v_max3_f32 v64, v64, v69, v70
	v_cndmask_b32_e32 v71, v65, v131, vcc
	v_cndmask_b32_e32 v76, v153, v131, vcc
	s_waitcnt lgkmcnt(13)
	v_fmamk_f32 v65, v72, 0x3e0293ee, v158
	v_fmac_f32_e32 v159, 0x3e0293ee, v73
	s_cmpk_lt_u32 s85, 0x100
	v_max3_f32 v64, v64, v71, v76
	v_cndmask_b32_e32 v72, v65, v131, vcc
	v_cndmask_b32_e32 v73, v159, v131, vcc
	s_waitcnt lgkmcnt(12)
	v_fmamk_f32 v65, v74, 0x3e0293ee, v160
	v_fmac_f32_e32 v161, 0x3e0293ee, v75
	s_cselect_b64 s[86:87], -1, 0
	v_max3_f32 v64, v64, v72, v73
	v_cndmask_b32_e32 v74, v65, v131, vcc
	v_cndmask_b32_e32 v75, v161, v131, vcc
	s_waitcnt lgkmcnt(11)
	v_fmamk_f32 v65, v138, 0x3e0293ee, v162
	s_and_b64 vcc, s[30:31], s[86:87]
	v_fmac_f32_e32 v163, 0x3e0293ee, v139
	v_max3_f32 v64, v64, v74, v75
	v_cndmask_b32_e32 v77, v65, v131, vcc
	v_cndmask_b32_e32 v78, v163, v131, vcc
	s_waitcnt lgkmcnt(10)
	v_fmamk_f32 v65, v140, 0x3e0293ee, v164
	v_fmac_f32_e32 v165, 0x3e0293ee, v141
	v_max3_f32 v64, v64, v77, v78
	v_cndmask_b32_e32 v79, v65, v131, vcc
	v_cndmask_b32_e32 v83, v165, v131, vcc
	s_waitcnt lgkmcnt(9)
	v_fmamk_f32 v65, v134, 0x3e0293ee, v166
	v_fmac_f32_e32 v167, 0x3e0293ee, v135
	s_cmpk_lt_u32 s85, 0x80
	v_max3_f32 v64, v64, v79, v83
	v_cndmask_b32_e32 v85, v65, v131, vcc
	v_cndmask_b32_e32 v133, v167, v131, vcc
	s_waitcnt lgkmcnt(8)
	v_fmamk_f32 v65, v136, 0x3e0293ee, v168
	v_fmac_f32_e32 v169, 0x3e0293ee, v137
	s_cselect_b64 s[84:85], -1, 0
	v_max3_f32 v64, v64, v85, v133
	v_cndmask_b32_e32 v134, v65, v131, vcc
	v_cndmask_b32_e32 v135, v169, v131, vcc
	s_waitcnt lgkmcnt(7)
	v_fmamk_f32 v65, v146, 0x3e0293ee, v170
	s_and_b64 vcc, s[30:31], s[84:85]
	v_fmac_f32_e32 v171, 0x3e0293ee, v147
	v_max3_f32 v64, v64, v134, v135
	v_cndmask_b32_e32 v136, v65, v131, vcc
	v_cndmask_b32_e32 v137, v171, v131, vcc
	s_waitcnt lgkmcnt(6)
	v_fmamk_f32 v65, v148, 0x3e0293ee, v172
	v_fmac_f32_e32 v173, 0x3e0293ee, v149
	v_max3_f32 v64, v64, v136, v137
	v_cndmask_b32_e32 v138, v65, v131, vcc
	v_cndmask_b32_e32 v139, v173, v131, vcc
	s_waitcnt lgkmcnt(5)
	v_fmamk_f32 v65, v142, 0x3e0293ee, v174
	v_fmac_f32_e32 v175, 0x3e0293ee, v143
	v_max3_f32 v64, v64, v138, v139
	v_cndmask_b32_e32 v140, v65, v131, vcc
	v_cndmask_b32_e32 v141, v175, v131, vcc
	s_waitcnt lgkmcnt(4)
	v_fmamk_f32 v65, v144, 0x3e0293ee, v176
	v_fmac_f32_e32 v177, 0x3e0293ee, v145
	v_max3_f32 v64, v64, v140, v141
	v_cndmask_b32_e32 v142, v65, v131, vcc
	v_cndmask_b32_e32 v143, v177, v131, vcc
	v_max3_f32 v64, v64, v142, v143
	s_waitcnt lgkmcnt(3)
	v_fmamk_f32 v88, v154, 0x3e0293ee, v88
	v_fmac_f32_e32 v89, 0x3e0293ee, v155
	s_waitcnt lgkmcnt(0)
	v_fmamk_f32 v48, v54, 0x3e0293ee, v48
	v_and_b32_e32 v54, 64, v132
	v_max3_f32 v64, v64, v88, v89
	v_fmamk_f32 v86, v156, 0x3e0293ee, v86
	v_fmac_f32_e32 v87, 0x3e0293ee, v157
	v_fmac_f32_e32 v51, 0x3e0293ee, v53
	v_xor_b32_e32 v53, 16, v132
	v_add_u32_e32 v54, 64, v54
	v_max3_f32 v64, v64, v86, v87
	v_fmamk_f32 v50, v52, 0x3e0293ee, v50
	v_cmp_lt_i32_e32 vcc, v53, v54
	v_max3_f32 v52, v64, v50, v51
	v_fmac_f32_e32 v49, 0x3e0293ee, v55
	v_cndmask_b32_e32 v53, v132, v53, vcc
	v_max3_f32 v52, v52, v48, v49
	v_lshlrev_b32_e32 v144, 2, v53
	ds_bpermute_b32 v53, v144, v52
	s_or_b32 s62, s62, s11
	s_waitcnt lgkmcnt(0)
	v_max_f32_e32 v53, v53, v53
	v_max_f32_e32 v52, v52, v53
	v_xor_b32_e32 v53, 32, v132
	v_cmp_lt_i32_e32 vcc, v53, v54
	v_or_b32_e32 v54, s81, v92
	v_add_u32_e32 v80, s54, v54
	v_cndmask_b32_e32 v53, v132, v53, vcc
	v_lshlrev_b32_e32 v145, 2, v53
	ds_bpermute_b32 v53, v145, v52
	s_waitcnt lgkmcnt(0)
; __device__ __forceinline__ unsigned cvtpk(float lo, float hi) { f32x2_t v = {lo, hi}; bf16x2_t b = __builtin_convertvector(v, bf16x2_t); return __builtin_bit_cast(unsigned, b); }
; #define ATT_VLOAD(kk_, buf_) do { const unsigned r0_ = 32 * (ks0 + (kk_)) + 8 * kg + q4; _Pragma("unroll") for (int c = 0; c < 8; ++c) { \
;         vlo[buf_][c] = vtr(vbase + ((off_b(r0_, 2 * c + (p4 >> 1)) + 8 * (p4 & 1)) ^ par)); vhi[buf_][c] = vtr(vbase + ((off_b(r0_ + 4, 2 * c + (p4 >> 1)) + 8 * (p4 & 1)) ^ par)); } } while (0)
; __device__ __forceinline__ void attn_compute(LAS unsigned char* lds, const bf16x8 (&qf)[4], const AttnUnit& u, bf16* og, float* lse) {
;     ...
;     float l = 0.f;
;     bf16x8 pf[5];
; #pragma unroll
;     for (int kk = 0; kk < 5; ++kk) {
;         float e[8];
; #pragma unroll
;         for (int T = 0; T < 2; ++T)
; #pragma unroll
;             for (int jj = 0; jj < 4; ++jj) { const float p = __builtin_amdgcn_exp2f(sc[kk][T][jj] - mx); e[4 * T + jj] = p; l += p; }
;         v4u pw; pw.x = cvtpk(e[0], e[1]); pw.y = cvtpk(e[2], e[3]); pw.z = cvtpk(e[4], e[5]); pw.w = cvtpk(e[6], e[7]);
;         pf[kk] = __builtin_bit_cast(bf16x8, pw);
;     }
;     l += __shfl_xor(l, 16); l += __shfl_xor(l, 32);
;     f32x4 o[8];
; #pragma unroll
;     for (int c = 0; c < 8; ++c) o[c] = (f32x4){0.f, 0.f, 0.f, 0.f};
;     const unsigned vbase = (unsigned)(uintptr_t)Vs;
;     const unsigned q4 = (lane & 15) >> 2, p4 = lane & 3;
;     s16x4 vlo[2][8], vhi[2][8];
;     ...
;     ATT_VLOAD(0, 0);
; #pragma unroll
;     for (int kk = 0; kk < 5; ++kk) {
;         if (kk < 4) ATT_VLOAD(kk + 1, (kk + 1) & 1);
	v_max_f32_e32 v53, v53, v53
	v_max_f32_e32 v68, v52, v53
	v_sub_f32_e32 v52, v56, v68
	v_exp_f32_e32 v52, v52
	v_sub_f32_e32 v53, v57, v68
	v_exp_f32_e32 v53, v53
	v_sub_f32_e32 v54, v58, v68
	v_exp_f32_e32 v54, v54
	v_sub_f32_e32 v55, v59, v68
	v_exp_f32_e32 v55, v55
	v_sub_f32_e32 v57, v60, v68
	v_add_f32_e32 v56, 0, v52
	v_exp_f32_e32 v57, v57
	v_sub_f32_e32 v58, v61, v68
	v_add_f32_e32 v56, v53, v56
	v_exp_f32_e32 v58, v58
	v_sub_f32_e32 v59, v62, v68
	v_add_f32_e32 v56, v54, v56
	v_exp_f32_e32 v59, v59
	v_sub_f32_e32 v60, v63, v68
	v_add_f32_e32 v56, v55, v56
	v_exp_f32_e32 v60, v60
	v_cvt_pk_bf16_f32 v64, v52, v53
	v_sub_f32_e32 v52, v69, v68
	v_add_f32_e32 v56, v57, v56
	v_exp_f32_e32 v52, v52
	v_sub_f32_e32 v53, v70, v68
	v_add_f32_e32 v56, v58, v56
	v_cvt_pk_bf16_f32 v65, v54, v55
	v_exp_f32_e32 v53, v53
	v_sub_f32_e32 v54, v71, v68
	v_add_f32_e32 v56, v59, v56
	v_exp_f32_e32 v54, v54
	v_sub_f32_e32 v55, v76, v68
	v_add_f32_e32 v56, v60, v56
	v_cvt_pk_bf16_f32 v66, v57, v58
	v_exp_f32_e32 v55, v55
	v_sub_f32_e32 v57, v72, v68
	v_add_f32_e32 v56, v52, v56
	v_exp_f32_e32 v57, v57
	v_sub_f32_e32 v58, v73, v68
	v_cvt_pk_bf16_f32 v67, v59, v60
	v_add_f32_e32 v56, v53, v56
	v_exp_f32_e32 v58, v58
	v_sub_f32_e32 v59, v74, v68
	v_add_f32_e32 v56, v54, v56
	v_exp_f32_e32 v59, v59
	v_sub_f32_e32 v60, v75, v68
	v_add_f32_e32 v56, v55, v56
	v_exp_f32_e32 v63, v60
	v_cvt_pk_bf16_f32 v60, v52, v53
	v_sub_f32_e32 v52, v77, v68
	v_add_f32_e32 v56, v57, v56
	v_exp_f32_e32 v52, v52
	v_sub_f32_e32 v53, v78, v68
	v_add_f32_e32 v56, v58, v56
	v_cvt_pk_bf16_f32 v61, v54, v55
	v_exp_f32_e32 v53, v53
	v_sub_f32_e32 v54, v79, v68
	v_add_f32_e32 v56, v59, v56
	v_exp_f32_e32 v54, v54
	v_sub_f32_e32 v55, v83, v68
	v_add_f32_e32 v56, v63, v56
	v_cvt_pk_bf16_f32 v62, v57, v58
	v_exp_f32_e32 v55, v55
	v_sub_f32_e32 v57, v85, v68
	v_add_f32_e32 v56, v52, v56
	v_exp_f32_e32 v58, v57
	v_sub_f32_e32 v57, v133, v68
	v_cvt_pk_bf16_f32 v63, v59, v63
	v_add_f32_e32 v56, v53, v56
	v_exp_f32_e32 v59, v57
	v_sub_f32_e32 v57, v134, v68
	v_add_f32_e32 v56, v54, v56
	v_exp_f32_e32 v69, v57
	v_sub_f32_e32 v57, v135, v68
	v_add_f32_e32 v56, v55, v56
	v_exp_f32_e32 v70, v57
	v_add_f32_e32 v56, v58, v56
	v_add_f32_e32 v56, v59, v56
	v_add_f32_e32 v56, v69, v56
	v_add_f32_e32 v71, v70, v56
	v_cvt_pk_bf16_f32 v56, v52, v53
	v_sub_f32_e32 v52, v136, v68
	v_exp_f32_e32 v52, v52
	v_sub_f32_e32 v53, v137, v68
	v_cvt_pk_bf16_f32 v57, v54, v55
	v_exp_f32_e32 v53, v53
	v_sub_f32_e32 v54, v138, v68
	v_exp_f32_e32 v54, v54
	v_sub_f32_e32 v55, v139, v68
	v_cvt_pk_bf16_f32 v58, v58, v59
	v_cvt_pk_bf16_f32 v59, v69, v70
	v_exp_f32_e32 v55, v55
	v_add_f32_e32 v69, v52, v71
	v_sub_f32_e32 v70, v140, v68
	v_sub_f32_e32 v71, v141, v68
	v_exp_f32_e32 v70, v70
	v_exp_f32_e32 v71, v71
	v_add_f32_e32 v69, v53, v69
	v_sub_f32_e32 v72, v142, v68
	v_sub_f32_e32 v73, v143, v68
	v_add_f32_e32 v69, v54, v69
	v_exp_f32_e32 v72, v72
	v_exp_f32_e32 v73, v73
	v_add_f32_e32 v69, v55, v69
	v_add_f32_e32 v69, v70, v69
	v_cvt_pk_bf16_f32 v52, v52, v53
	v_cvt_pk_bf16_f32 v53, v54, v55
	v_cvt_pk_bf16_f32 v54, v70, v71
	v_sub_f32_e32 v70, v88, v68
	v_add_f32_e32 v69, v71, v69
	v_exp_f32_e32 v70, v70
	v_sub_f32_e32 v71, v89, v68
	v_add_f32_e32 v69, v72, v69
	v_cvt_pk_bf16_f32 v55, v72, v73
	v_exp_f32_e32 v71, v71
	v_sub_f32_e32 v72, v86, v68
	v_add_f32_e32 v69, v73, v69
	v_exp_f32_e32 v72, v72
	v_sub_f32_e32 v73, v87, v68
	v_exp_f32_e32 v73, v73
	v_sub_f32_e32 v50, v50, v68
	v_add_f32_e32 v69, v70, v69
	v_exp_f32_e32 v50, v50
	v_sub_f32_e32 v51, v51, v68
	v_add_f32_e32 v69, v71, v69
	v_exp_f32_e32 v51, v51
	v_sub_f32_e32 v48, v48, v68
	v_add_f32_e32 v69, v72, v69
	v_exp_f32_e32 v74, v48
	v_sub_f32_e32 v48, v49, v68
	v_add_f32_e32 v69, v73, v69
	v_exp_f32_e32 v75, v48
	v_add_f32_e32 v48, v50, v69
	v_add_f32_e32 v48, v51, v48
	v_add_f32_e32 v48, v74, v48
	v_add_f32_e32 v69, v75, v48
	v_cvt_pk_bf16_f32 v48, v70, v71
	v_or_b32_e32 v71, s83, v111
	v_lshl_or_b32 v83, v71, 8, v114
	v_or_b32_e32 v71, 4, v71
	v_bitop3_b32 v133, v83, s77, v121 bitop3:0x36
	v_bfe_u32 v85, v71, 2, 2
	v_add_u32_e32 v133, s73, v133
	ds_read_b64_tr_b16 v[134:135], v133
	v_bitop3_b32 v133, v85, v120, v113 bitop3:0x36
	v_lshl_or_b32 v71, v71, 8, v114
	v_lshlrev_b32_e32 v133, 4, v133
	v_bitop3_b32 v133, v133, s77, v71 bitop3:0x36
	v_add_u32_e32 v133, s73, v133
	ds_read_b64_tr_b16 v[136:137], v133
	v_bitop3_b32 v133, v83, s77, v123 bitop3:0x36
	v_add_u32_e32 v133, s73, v133
	ds_read_b64_tr_b16 v[138:139], v133
	v_bitop3_b32 v133, v85, v122, v113 bitop3:0x36
	v_lshlrev_b32_e32 v133, 4, v133
	v_bitop3_b32 v133, v133, s77, v71 bitop3:0x36
	v_add_u32_e32 v133, s73, v133
	ds_bpermute_b32 v76, v144, v69
	ds_read_b64_tr_b16 v[140:141], v133
	v_bitop3_b32 v133, v83, s77, v126 bitop3:0x36
	v_add_u32_e32 v133, s73, v133
	ds_read_b64_tr_b16 v[142:143], v133
	v_bitop3_b32 v133, v85, v124, v113 bitop3:0x36
	v_lshlrev_b32_e32 v133, 4, v133
	v_bitop3_b32 v133, v133, s77, v71 bitop3:0x36
	s_waitcnt lgkmcnt(2)
; #define ATT_VLOAD(kk_, buf_) do { const unsigned r0_ = 32 * (ks0 + (kk_)) + 8 * kg + q4; _Pragma("unroll") for (int c = 0; c < 8; ++c) { \
;         vlo[buf_][c] = vtr(vbase + ((off_b(r0_, 2 * c + (p4 >> 1)) + 8 * (p4 & 1)) ^ par)); vhi[buf_][c] = vtr(vbase + ((off_b(r0_ + 4, 2 * c + (p4 >> 1)) + 8 * (p4 & 1)) ^ par)); } } while (0)
; __device__ __forceinline__ void attn_compute(LAS unsigned char* lds, const bf16x8 (&qf)[4], const AttnUnit& u, bf16* og, float* lse) {
;     ...
;     const unsigned vbase = (unsigned)(uintptr_t)Vs;
;     const unsigned q4 = (lane & 15) >> 2, p4 = lane & 3;
;     s16x4 vlo[2][8], vhi[2][8];
;     ...
;     ATT_VLOAD(0, 0);
; #pragma unroll
;     for (int kk = 0; kk < 5; ++kk) {
;         if (kk < 4) ATT_VLOAD(kk + 1, (kk + 1) & 1);
; #pragma unroll
;         for (int c = 0; c < 8; ++c) {
;             const s16x4 lo = vlo[kk & 1][c], hi = vhi[kk & 1][c];
;             const bf16x8 vf = (bf16x8){lo[0], lo[1], lo[2], lo[3], hi[0], hi[1], hi[2], hi[3]};
;             o[c] = __builtin_amdgcn_mfma_f32_16x16x32_bf16(vf, pf[kk], o[c], 0, 0, 0);
;         }
;     }
	v_add_f32_e32 v69, v69, v76
	v_add_u32_e32 v133, s73, v133
	v_cvt_pk_bf16_f32 v49, v72, v73
	ds_bpermute_b32 v70, v145, v69
	v_bitop3_b32 v72, v83, s77, v115 bitop3:0x36
	v_bitop3_b32 v76, v83, s77, v117 bitop3:0x36
	v_bitop3_b32 v86, v83, s77, v119 bitop3:0x36
	ds_read_b64_tr_b16 v[144:145], v133
	v_bitop3_b32 v133, v83, s77, v128 bitop3:0x36
	v_bitop3_b32 v83, v83, s77, v130 bitop3:0x36
	v_add_u32_e32 v133, s73, v133
	v_add_u32_e32 v83, s73, v83
	v_cvt_pk_bf16_f32 v50, v50, v51
	v_cvt_pk_bf16_f32 v51, v74, v75
	v_bitop3_b32 v74, v85, v112, v113 bitop3:0x36
	v_bitop3_b32 v78, v85, v116, v113 bitop3:0x36
	v_bitop3_b32 v88, v85, v118, v113 bitop3:0x36
	ds_read_b64_tr_b16 v[146:147], v133
	v_bitop3_b32 v133, v85, v127, v113 bitop3:0x36
	ds_read_b64_tr_b16 v[150:151], v83
	v_bitop3_b32 v83, v85, v129, v113 bitop3:0x36
	v_lshlrev_b32_e32 v74, 4, v74
	v_lshlrev_b32_e32 v78, 4, v78
	v_lshlrev_b32_e32 v88, 4, v88
	v_lshlrev_b32_e32 v133, 4, v133
	v_lshlrev_b32_e32 v83, 4, v83
	v_bitop3_b32 v74, v74, s77, v71 bitop3:0x36
	v_bitop3_b32 v78, v78, s77, v71 bitop3:0x36
	v_bitop3_b32 v88, v88, s77, v71 bitop3:0x36
	v_bitop3_b32 v133, v133, s77, v71 bitop3:0x36
	v_bitop3_b32 v71, v83, s77, v71 bitop3:0x36
	v_add_u32_e32 v71, s73, v71
	ds_read_b64_tr_b16 v[152:153], v71
	v_or_b32_e32 v71, s82, v111
	v_add_u32_e32 v133, s73, v133
	v_lshl_or_b32 v83, v71, 8, v114
	ds_read_b64_tr_b16 v[148:149], v133
	v_or_b32_e32 v71, 4, v71
	v_bitop3_b32 v133, v83, s77, v115 bitop3:0x36
	v_bfe_u32 v85, v71, 2, 2
	v_add_u32_e32 v133, s73, v133
	ds_read_b64_tr_b16 v[154:155], v133
	v_bitop3_b32 v133, v85, v112, v113 bitop3:0x36
	v_lshl_or_b32 v71, v71, 8, v114
	v_lshlrev_b32_e32 v133, 4, v133
	v_bitop3_b32 v133, v133, s77, v71 bitop3:0x36
	v_add_u32_e32 v133, s73, v133
	ds_read_b64_tr_b16 v[156:157], v133
	v_bitop3_b32 v133, v83, s77, v117 bitop3:0x36
	v_add_u32_e32 v133, s73, v133
	ds_read_b64_tr_b16 v[158:159], v133
	v_bitop3_b32 v133, v85, v116, v113 bitop3:0x36
	v_lshlrev_b32_e32 v133, 4, v133
	v_bitop3_b32 v133, v133, s77, v71 bitop3:0x36
	v_add_u32_e32 v133, s73, v133
	ds_read_b64_tr_b16 v[160:161], v133
	v_bitop3_b32 v133, v83, s77, v119 bitop3:0x36
	v_add_u32_e32 v133, s73, v133
	ds_read_b64_tr_b16 v[162:163], v133
	v_bitop3_b32 v133, v85, v118, v113 bitop3:0x36
	v_lshlrev_b32_e32 v133, 4, v133
	v_bitop3_b32 v133, v133, s77, v71 bitop3:0x36
	v_add_u32_e32 v133, s73, v133
	ds_read_b64_tr_b16 v[164:165], v133
	v_bitop3_b32 v133, v83, s77, v121 bitop3:0x36
	v_add_u32_e32 v133, s73, v133
	ds_read_b64_tr_b16 v[166:167], v133
	v_bitop3_b32 v133, v85, v120, v113 bitop3:0x36
	v_lshlrev_b32_e32 v133, 4, v133
	v_bitop3_b32 v133, v133, s77, v71 bitop3:0x36
	v_add_u32_e32 v133, s73, v133
	ds_read_b64_tr_b16 v[168:169], v133
	v_bitop3_b32 v133, v83, s77, v123 bitop3:0x36
	v_add_u32_e32 v133, s73, v133
	ds_read_b64_tr_b16 v[170:171], v133
	v_bitop3_b32 v133, v85, v122, v113 bitop3:0x36
	v_lshlrev_b32_e32 v133, 4, v133
	v_bitop3_b32 v133, v133, s77, v71 bitop3:0x36
	v_add_u32_e32 v133, s73, v133
	ds_read_b64_tr_b16 v[172:173], v133
	v_bitop3_b32 v133, v83, s77, v126 bitop3:0x36
	v_add_u32_e32 v133, s73, v133
	ds_read_b64_tr_b16 v[174:175], v133
	v_bitop3_b32 v133, v85, v124, v113 bitop3:0x36
	v_lshlrev_b32_e32 v133, 4, v133
	v_bitop3_b32 v133, v133, s77, v71 bitop3:0x36
	v_add_u32_e32 v133, s73, v133
	v_add_u32_e32 v72, s73, v72
	v_add_u32_e32 v74, s73, v74
	v_add_u32_e32 v76, s73, v76
	v_add_u32_e32 v78, s73, v78
	v_add_u32_e32 v86, s73, v86
	v_add_u32_e32 v88, s73, v88
	ds_read_b64_tr_b16 v[176:177], v133
	v_bitop3_b32 v133, v83, s77, v128 bitop3:0x36
	v_bitop3_b32 v83, v83, s77, v130 bitop3:0x36
	ds_read_b64_tr_b16 v[72:73], v72
	ds_read_b64_tr_b16 v[74:75], v74
	ds_read_b64_tr_b16 v[76:77], v76
	ds_read_b64_tr_b16 v[78:79], v78
	ds_read_b64_tr_b16 v[86:87], v86
	ds_read_b64_tr_b16 v[88:89], v88
	v_add_u32_e32 v133, s73, v133
	v_add_u32_e32 v83, s73, v83
	ds_read_b64_tr_b16 v[180:181], v133
	v_bitop3_b32 v133, v85, v127, v113 bitop3:0x36
	ds_read_b64_tr_b16 v[184:185], v83
	v_bitop3_b32 v83, v85, v129, v113 bitop3:0x36
	v_lshlrev_b32_e32 v133, 4, v133
	v_lshlrev_b32_e32 v83, 4, v83
	v_bitop3_b32 v133, v133, s77, v71 bitop3:0x36
	v_bitop3_b32 v71, v83, s77, v71 bitop3:0x36
	v_add_u32_e32 v71, s73, v71
	ds_read_b64_tr_b16 v[186:187], v71
	v_or_b32_e32 v71, s80, v111
	v_add_u32_e32 v133, s73, v133
	v_lshl_or_b32 v83, v71, 8, v114
	ds_read_b64_tr_b16 v[182:183], v133
	v_or_b32_e32 v71, 4, v71
	v_bitop3_b32 v133, v83, s77, v115 bitop3:0x36
	v_bfe_u32 v85, v71, 2, 2
	v_add_u32_e32 v133, s73, v133
	s_waitcnt lgkmcnt(8)
	v_mfma_f32_16x16x32_bf16 v[72:75], v[72:75], v[64:67], 0
	v_lshl_or_b32 v71, v71, 8, v114
	s_waitcnt lgkmcnt(6)
	v_mfma_f32_16x16x32_bf16 v[76:79], v[76:79], v[64:67], 0
	s_waitcnt lgkmcnt(4)
; #define ATT_VLOAD(kk_, buf_) do { const unsigned r0_ = 32 * (ks0 + (kk_)) + 8 * kg + q4; _Pragma("unroll") for (int c = 0; c < 8; ++c) { \
;         vlo[buf_][c] = vtr(vbase + ((off_b(r0_, 2 * c + (p4 >> 1)) + 8 * (p4 & 1)) ^ par)); vhi[buf_][c] = vtr(vbase + ((off_b(r0_ + 4, 2 * c + (p4 >> 1)) + 8 * (p4 & 1)) ^ par)); } } while (0)
; __device__ __forceinline__ void attn_compute(LAS unsigned char* lds, const bf16x8 (&qf)[4], const AttnUnit& u, bf16* og, float* lse) {
;     ...
;     const unsigned vbase = (unsigned)(uintptr_t)Vs;
;     const unsigned q4 = (lane & 15) >> 2, p4 = lane & 3;
;     s16x4 vlo[2][8], vhi[2][8];
;     ...
;     ATT_VLOAD(0, 0);
; #pragma unroll
;     for (int kk = 0; kk < 5; ++kk) {
;         if (kk < 4) ATT_VLOAD(kk + 1, (kk + 1) & 1);
; #pragma unroll
;         for (int c = 0; c < 8; ++c) {
;             const s16x4 lo = vlo[kk & 1][c], hi = vhi[kk & 1][c];
;             const bf16x8 vf = (bf16x8){lo[0], lo[1], lo[2], lo[3], hi[0], hi[1], hi[2], hi[3]};
;             o[c] = __builtin_amdgcn_mfma_f32_16x16x32_bf16(vf, pf[kk], o[c], 0, 0, 0);
;         }
;     }
	v_mfma_f32_16x16x32_bf16 v[86:89], v[86:89], v[64:67], 0
	v_mfma_f32_16x16x32_bf16 v[134:137], v[134:137], v[64:67], 0
	v_mfma_f32_16x16x32_bf16 v[138:141], v[138:141], v[64:67], 0
	v_mfma_f32_16x16x32_bf16 v[142:145], v[142:145], v[64:67], 0
	v_mfma_f32_16x16x32_bf16 v[146:149], v[146:149], v[64:67], 0
	v_mfma_f32_16x16x32_bf16 v[64:67], v[150:153], v[64:67], 0
	ds_read_b64_tr_b16 v[150:151], v133
	v_bitop3_b32 v133, v85, v112, v113 bitop3:0x36
	v_lshlrev_b32_e32 v133, 4, v133
	v_bitop3_b32 v133, v133, s77, v71 bitop3:0x36
	v_add_u32_e32 v133, s73, v133
	ds_read_b64_tr_b16 v[152:153], v133
	v_bitop3_b32 v133, v83, s77, v117 bitop3:0x36
	v_add_u32_e32 v133, s73, v133
	ds_read_b64_tr_b16 v[188:189], v133
	v_bitop3_b32 v133, v85, v116, v113 bitop3:0x36
	v_lshlrev_b32_e32 v133, 4, v133
	v_bitop3_b32 v133, v133, s77, v71 bitop3:0x36
	v_add_u32_e32 v133, s73, v133
	ds_read_b64_tr_b16 v[190:191], v133
	v_bitop3_b32 v133, v83, s77, v119 bitop3:0x36
	v_add_u32_e32 v133, s73, v133
	ds_read_b64_tr_b16 v[192:193], v133
	v_bitop3_b32 v133, v85, v118, v113 bitop3:0x36
	v_lshlrev_b32_e32 v133, 4, v133
	v_bitop3_b32 v133, v133, s77, v71 bitop3:0x36
	v_add_u32_e32 v133, s73, v133
	ds_read_b64_tr_b16 v[194:195], v133
	v_bitop3_b32 v133, v83, s77, v121 bitop3:0x36
	v_add_u32_e32 v133, s73, v133
	ds_read_b64_tr_b16 v[196:197], v133
	v_bitop3_b32 v133, v85, v120, v113 bitop3:0x36
	v_lshlrev_b32_e32 v133, 4, v133
	v_bitop3_b32 v133, v133, s77, v71 bitop3:0x36
	v_add_u32_e32 v133, s73, v133
	ds_read_b64_tr_b16 v[198:199], v133
	v_bitop3_b32 v133, v83, s77, v123 bitop3:0x36
	v_add_u32_e32 v133, s73, v133
	ds_read_b64_tr_b16 v[200:201], v133
	v_bitop3_b32 v133, v85, v122, v113 bitop3:0x36
	v_lshlrev_b32_e32 v133, 4, v133
	v_bitop3_b32 v133, v133, s77, v71 bitop3:0x36
	v_add_u32_e32 v133, s73, v133
	ds_read_b64_tr_b16 v[202:203], v133
	v_bitop3_b32 v133, v83, s77, v126 bitop3:0x36
	v_add_u32_e32 v133, s73, v133
	ds_read_b64_tr_b16 v[204:205], v133
	v_bitop3_b32 v133, v85, v124, v113 bitop3:0x36
	v_lshlrev_b32_e32 v133, 4, v133
	v_bitop3_b32 v133, v133, s77, v71 bitop3:0x36
	v_add_u32_e32 v133, s73, v133
	ds_read_b64_tr_b16 v[206:207], v133
	v_bitop3_b32 v133, v83, s77, v128 bitop3:0x36
	v_bitop3_b32 v83, v83, s77, v130 bitop3:0x36
	v_add_u32_e32 v133, s73, v133
	v_add_u32_e32 v83, s73, v83
	v_mfma_f32_16x16x32_bf16 v[72:75], v[154:157], v[60:63], v[72:75]
	ds_read_b64_tr_b16 v[154:155], v133
	v_bitop3_b32 v133, v85, v127, v113 bitop3:0x36
	v_lshlrev_b32_e32 v133, 4, v133
	v_mfma_f32_16x16x32_bf16 v[76:79], v[158:161], v[60:63], v[76:79]
	ds_read_b64_tr_b16 v[158:159], v83
	v_bitop3_b32 v83, v85, v129, v113 bitop3:0x36
	v_lshlrev_b32_e32 v83, 4, v83
	v_bitop3_b32 v133, v133, s77, v71 bitop3:0x36
	v_bitop3_b32 v71, v83, s77, v71 bitop3:0x36
	v_mfma_f32_16x16x32_bf16 v[86:89], v[162:165], v[60:63], v[86:89]
	v_add_u32_e32 v71, s73, v71
	v_add_u32_e32 v133, s73, v133
	ds_read_b64_tr_b16 v[160:161], v71
	v_mfma_f32_16x16x32_bf16 v[134:137], v[166:169], v[60:63], v[134:137]
	ds_read_b64_tr_b16 v[156:157], v133
	v_mfma_f32_16x16x32_bf16 v[138:141], v[170:173], v[60:63], v[138:141]
	v_mfma_f32_16x16x32_bf16 v[142:145], v[174:177], v[60:63], v[142:145]
	s_waitcnt lgkmcnt(14)
	v_mfma_f32_16x16x32_bf16 v[146:149], v[180:183], v[60:63], v[146:149]
	v_mfma_f32_16x16x32_bf16 v[60:63], v[184:187], v[60:63], v[64:67]
	s_nop 2
	v_or_b32_e32 v64, s79, v111
	v_lshl_or_b32 v71, v64, 8, v114
	v_or_b32_e32 v64, 4, v64
	v_bitop3_b32 v133, v71, s77, v117 bitop3:0x36
	v_bfe_u32 v83, v64, 2, 2
	v_add_u32_e32 v133, s73, v133
	ds_read_b64_tr_b16 v[162:163], v133
	v_bitop3_b32 v133, v83, v116, v113 bitop3:0x36
	v_lshl_or_b32 v85, v64, 8, v114
	v_lshlrev_b32_e32 v133, 4, v133
	v_bitop3_b32 v133, v133, s77, v85 bitop3:0x36
	v_add_u32_e32 v133, s73, v133
	ds_read_b64_tr_b16 v[164:165], v133
	v_bitop3_b32 v133, v71, s77, v119 bitop3:0x36
	v_add_u32_e32 v133, s73, v133
	ds_read_b64_tr_b16 v[166:167], v133
	v_bitop3_b32 v133, v83, v118, v113 bitop3:0x36
	v_lshlrev_b32_e32 v133, 4, v133
	v_bitop3_b32 v133, v133, s77, v85 bitop3:0x36
	v_add_u32_e32 v133, s73, v133
	ds_read_b64_tr_b16 v[168:169], v133
	v_bitop3_b32 v133, v71, s77, v121 bitop3:0x36
	v_add_u32_e32 v133, s73, v133
	ds_read_b64_tr_b16 v[170:171], v133
	v_bitop3_b32 v133, v83, v120, v113 bitop3:0x36
	v_lshlrev_b32_e32 v133, 4, v133
	v_bitop3_b32 v133, v133, s77, v85 bitop3:0x36
	v_add_u32_e32 v133, s73, v133
	ds_read_b64_tr_b16 v[172:173], v133
	v_bitop3_b32 v133, v71, s77, v123 bitop3:0x36
	v_add_u32_e32 v133, s73, v133
	ds_read_b64_tr_b16 v[174:175], v133
	v_bitop3_b32 v133, v83, v122, v113 bitop3:0x36
	v_lshlrev_b32_e32 v133, 4, v133
	v_bitop3_b32 v133, v133, s77, v85 bitop3:0x36
	v_add_u32_e32 v133, s73, v133
	ds_read_b64_tr_b16 v[176:177], v133
	v_bitop3_b32 v133, v71, s77, v126 bitop3:0x36
	v_add_u32_e32 v133, s73, v133
	ds_read_b64_tr_b16 v[180:181], v133
	v_bitop3_b32 v133, v83, v124, v113 bitop3:0x36
	v_lshlrev_b32_e32 v133, 4, v133
	v_bitop3_b32 v133, v133, s77, v85 bitop3:0x36
	v_add_u32_e32 v133, s73, v133
	v_bitop3_b32 v64, v71, s77, v115 bitop3:0x36
	ds_read_b64_tr_b16 v[182:183], v133
	v_bitop3_b32 v133, v71, s77, v128 bitop3:0x36
	v_bitop3_b32 v71, v71, s77, v130 bitop3:0x36
	v_add_u32_e32 v71, s73, v71
	v_add_u32_e32 v133, s73, v133
	ds_read_b64_tr_b16 v[184:185], v71
	v_bitop3_b32 v71, v83, v129, v113 bitop3:0x36
	v_mfma_f32_16x16x32_bf16 v[72:75], v[150:153], v[56:59], v[72:75]
	ds_read_b64_tr_b16 v[150:151], v133
	v_bitop3_b32 v133, v83, v127, v113 bitop3:0x36
	v_lshlrev_b32_e32 v71, 4, v71
	v_lshlrev_b32_e32 v133, 4, v133
	v_bitop3_b32 v71, v71, s77, v85 bitop3:0x36
	v_bitop3_b32 v66, v83, v112, v113 bitop3:0x36
	s_waitcnt lgkmcnt(14)
; #define ATT_VLOAD(kk_, buf_) do { const unsigned r0_ = 32 * (ks0 + (kk_)) + 8 * kg + q4; _Pragma("unroll") for (int c = 0; c < 8; ++c) { \
;         vlo[buf_][c] = vtr(vbase + ((off_b(r0_, 2 * c + (p4 >> 1)) + 8 * (p4 & 1)) ^ par)); vhi[buf_][c] = vtr(vbase + ((off_b(r0_ + 4, 2 * c + (p4 >> 1)) + 8 * (p4 & 1)) ^ par)); } } while (0)
; __device__ __forceinline__ void attn_compute(LAS unsigned char* lds, const bf16x8 (&qf)[4], const AttnUnit& u, bf16* og, float* lse) {
;     ...
;     const unsigned vbase = (unsigned)(uintptr_t)Vs;
;     const unsigned q4 = (lane & 15) >> 2, p4 = lane & 3;
;     s16x4 vlo[2][8], vhi[2][8];
;     ...
;     ATT_VLOAD(0, 0);
; #pragma unroll
;     for (int kk = 0; kk < 5; ++kk) {
;         if (kk < 4) ATT_VLOAD(kk + 1, (kk + 1) & 1);
; #pragma unroll
;         for (int c = 0; c < 8; ++c) {
;             const s16x4 lo = vlo[kk & 1][c], hi = vhi[kk & 1][c];
;             const bf16x8 vf = (bf16x8){lo[0], lo[1], lo[2], lo[3], hi[0], hi[1], hi[2], hi[3]};
;             o[c] = __builtin_amdgcn_mfma_f32_16x16x32_bf16(vf, pf[kk], o[c], 0, 0, 0);
;         }
;     }
	v_mfma_f32_16x16x32_bf16 v[76:79], v[188:191], v[56:59], v[76:79]
	v_bitop3_b32 v133, v133, s77, v85 bitop3:0x36
	v_add_u32_e32 v71, s73, v71
	v_lshlrev_b32_e32 v66, 4, v66
	v_mfma_f32_16x16x32_bf16 v[86:89], v[192:195], v[56:59], v[86:89]
	v_add_u32_e32 v133, s73, v133
	ds_read_b64_tr_b16 v[186:187], v71
	v_bitop3_b32 v66, v66, s77, v85 bitop3:0x36
	v_mfma_f32_16x16x32_bf16 v[134:137], v[196:199], v[56:59], v[134:137]
	ds_read_b64_tr_b16 v[152:153], v133
	v_add_u32_e32 v64, s73, v64
	v_add_u32_e32 v66, s73, v66
	v_mfma_f32_16x16x32_bf16 v[138:141], v[200:203], v[56:59], v[138:141]
	ds_read_b64_tr_b16 v[64:65], v64
	ds_read_b64_tr_b16 v[66:67], v66
	v_mfma_f32_16x16x32_bf16 v[142:145], v[204:207], v[56:59], v[142:145]
	s_waitcnt lgkmcnt(14)
	v_mfma_f32_16x16x32_bf16 v[146:149], v[154:157], v[56:59], v[146:149]
	v_mfma_f32_16x16x32_bf16 v[56:59], v[158:161], v[56:59], v[60:63]
	s_nop 2
	v_or_b32_e32 v60, s78, v111
	v_lshl_or_b32 v71, v60, 8, v114
	v_or_b32_e32 v60, 4, v60
	v_bitop3_b32 v133, v71, s77, v117 bitop3:0x36
	v_bfe_u32 v83, v60, 2, 2
	v_add_u32_e32 v133, s73, v133
	ds_read_b64_tr_b16 v[154:155], v133
	v_bitop3_b32 v133, v83, v116, v113 bitop3:0x36
	v_lshl_or_b32 v85, v60, 8, v114
	v_lshlrev_b32_e32 v133, 4, v133
	v_bitop3_b32 v133, v133, s77, v85 bitop3:0x36
	v_add_u32_e32 v133, s73, v133
	ds_read_b64_tr_b16 v[156:157], v133
	v_bitop3_b32 v133, v71, s77, v119 bitop3:0x36
	v_add_u32_e32 v133, s73, v133
	ds_read_b64_tr_b16 v[158:159], v133
	v_bitop3_b32 v133, v83, v118, v113 bitop3:0x36
	v_lshlrev_b32_e32 v133, 4, v133
	v_bitop3_b32 v133, v133, s77, v85 bitop3:0x36
	v_add_u32_e32 v133, s73, v133
	s_waitcnt lgkmcnt(3)
	v_mfma_f32_16x16x32_bf16 v[64:67], v[64:67], v[52:55], v[72:75]
	ds_read_b64_tr_b16 v[160:161], v133
	v_bitop3_b32 v62, v83, v112, v113 bitop3:0x36
	v_lshlrev_b32_e32 v62, 4, v62
	v_bitop3_b32 v72, v71, s77, v121 bitop3:0x36
	v_add_u32_e32 v133, s73, v72
	v_mfma_f32_16x16x32_bf16 v[72:75], v[162:165], v[52:55], v[76:79]
	v_bitop3_b32 v60, v71, s77, v115 bitop3:0x36
	v_bitop3_b32 v62, v62, s77, v85 bitop3:0x36
	v_add_u32_e32 v60, s73, v60
	ds_read_b64_tr_b16 v[76:77], v133
	v_bitop3_b32 v133, v71, s77, v123 bitop3:0x36
	v_add_u32_e32 v133, s73, v133
	ds_read_b64_tr_b16 v[162:163], v133
	v_bitop3_b32 v133, v83, v122, v113 bitop3:0x36
	v_lshlrev_b32_e32 v133, 4, v133
	v_bitop3_b32 v133, v133, s77, v85 bitop3:0x36
	v_add_u32_e32 v133, s73, v133
	v_add_u32_e32 v62, s73, v62
	ds_read_b64_tr_b16 v[164:165], v133
	v_bitop3_b32 v133, v71, s77, v126 bitop3:0x36
	ds_read_b64_tr_b16 v[60:61], v60
	ds_read_b64_tr_b16 v[62:63], v62
	v_add_u32_e32 v133, s73, v133
	v_mfma_f32_16x16x32_bf16 v[146:149], v[150:153], v[52:55], v[146:149]
	ds_read_b64_tr_b16 v[150:151], v133
	v_bitop3_b32 v133, v83, v124, v113 bitop3:0x36
	v_bitop3_b32 v78, v83, v120, v113 bitop3:0x36
	v_mfma_f32_16x16x32_bf16 v[86:89], v[166:169], v[52:55], v[86:89]
	v_lshlrev_b32_e32 v78, 4, v78
	v_bitop3_b32 v78, v78, s77, v85 bitop3:0x36
	v_add_u32_e32 v78, s73, v78
	v_mfma_f32_16x16x32_bf16 v[134:137], v[170:173], v[52:55], v[134:137]
	ds_read_b64_tr_b16 v[78:79], v78
	v_mfma_f32_16x16x32_bf16 v[138:141], v[174:177], v[52:55], v[138:141]
	v_mfma_f32_16x16x32_bf16 v[142:145], v[180:183], v[52:55], v[142:145]
	v_mfma_f32_16x16x32_bf16 v[56:59], v[184:187], v[52:55], v[56:59]
	v_lshlrev_b32_e32 v52, 4, v133
	v_bitop3_b32 v52, v52, s77, v85 bitop3:0x36
	v_bitop3_b32 v54, v83, v127, v113 bitop3:0x36
	v_add_u32_e32 v52, s73, v52
	v_lshlrev_b32_e32 v54, 4, v54
	ds_read_b64_tr_b16 v[152:153], v52
	v_bitop3_b32 v52, v71, s77, v128 bitop3:0x36
	v_bitop3_b32 v54, v54, s77, v85 bitop3:0x36
	v_add_u32_e32 v52, s73, v52
	v_add_u32_e32 v54, s73, v54
	ds_read_b64_tr_b16 v[52:53], v52
	ds_read_b64_tr_b16 v[54:55], v54
	v_bitop3_b32 v71, v71, s77, v130 bitop3:0x36
	v_add_u32_e32 v71, s73, v71
	s_waitcnt lgkmcnt(5)
; __device__ __forceinline__ unsigned cvtpk(float lo, float hi) { f32x2_t v = {lo, hi}; bf16x2_t b = __builtin_convertvector(v, bf16x2_t); return __builtin_bit_cast(unsigned, b); }
; __device__ __forceinline__ void attn_compute(LAS unsigned char* lds, const bf16x8 (&qf)[4], const AttnUnit& u, bf16* og, float* lse) {
;     ...
;         for (int c = 0; c < 8; ++c) {
;             const s16x4 lo = vlo[kk & 1][c], hi = vhi[kk & 1][c];
;             const bf16x8 vf = (bf16x8){lo[0], lo[1], lo[2], lo[3], hi[0], hi[1], hi[2], hi[3]};
;             o[c] = __builtin_amdgcn_mfma_f32_16x16x32_bf16(vf, pf[kk], o[c], 0, 0, 0);
;         }
;     }
;     ...
;     const float rl = 1.0f / l;
;     bf16* op = og + qtok * 1024 + h * 128 + 4 * kg;
; #pragma unroll
;     for (int c = 0; c < 8; ++c) { v2u wv; wv.x = cvtpk(o[c][0] * rl, o[c][1] * rl); wv.y = cvtpk(o[c][2] * rl, o[c][3] * rl); *(v2u*)(op + 16 * c) = wv; }
;     if (kg == 0) lse[qtok * 8 + h] = mx + __builtin_amdgcn_logf(l);
	v_mfma_f32_16x16x32_bf16 v[60:63], v[60:63], v[48:51], v[64:67]
	v_mfma_f32_16x16x32_bf16 v[64:67], v[154:157], v[48:51], v[72:75]
	v_mfma_f32_16x16x32_bf16 v[72:75], v[158:161], v[48:51], v[86:89]
	s_nop 2
	ds_read_b64_tr_b16 v[86:87], v71
	v_bitop3_b32 v71, v83, v129, v113 bitop3:0x36
	v_lshlrev_b32_e32 v71, 4, v71
	v_bitop3_b32 v71, v71, s77, v85 bitop3:0x36
	v_add_u32_e32 v71, s73, v71
	ds_read_b64_tr_b16 v[88:89], v71
	s_waitcnt lgkmcnt(5)
	v_mfma_f32_16x16x32_bf16 v[76:79], v[76:79], v[48:51], v[134:137]
	v_mov_b32_e32 v85, v81
	v_mfma_f32_16x16x32_bf16 v[134:137], v[162:165], v[48:51], v[138:141]
	s_waitcnt lgkmcnt(4)
	v_mfma_f32_16x16x32_bf16 v[138:141], v[150:153], v[48:51], v[142:145]
	v_lshlrev_b64 v[150:151], s8, v[80:81]
	s_lshl_b32 s8, s76, 8
	s_waitcnt lgkmcnt(2)
	v_mfma_f32_16x16x32_bf16 v[142:145], v[52:55], v[48:51], v[146:149]
	v_add_f32_e32 v54, v69, v70
	v_div_scale_f32 v55, s[30:31], v54, v54, 1.0
	v_rcp_f32_e32 v69, v55
	s_waitcnt lgkmcnt(0)
	v_mfma_f32_16x16x32_bf16 v[48:51], v[86:89], v[48:51], v[56:59]
	v_lshl_add_u64 v[52:53], s[62:63], 0, v[150:151]
	s_nop 1
	v_fma_f32 v56, -v55, v69, 1.0
	v_fmac_f32_e32 v69, v56, v69
	v_div_scale_f32 v56, vcc, 1.0, v54, 1.0
	v_mul_f32_e32 v57, v56, v69
	v_fma_f32 v58, -v55, v57, v56
	v_fmac_f32_e32 v57, v58, v69
	v_fma_f32 v55, -v55, v57, v56
	v_div_fmas_f32 v55, v55, v69, v57
	v_lshlrev_b64 v[58:59], 11, v[52:53]
	v_div_fixup_f32 v56, v55, v54, 1.0
	v_lshl_add_u64 v[58:59], s[60:61], 0, v[58:59]
	v_lshl_add_u64 v[58:59], v[58:59], 0, s[8:9]
	v_lshl_add_u64 v[58:59], v[58:59], 0, v[84:85]
	v_and_b32_e32 v224, 1, v99
	v_mul_u32_u24_e32 v224, 24, v224
	v_mov_b32_e32 v225, 0
	v_lshl_add_u64 v[58:59], v[224:225], 0, v[58:59]
	v_pk_mul_f32 v[60:61], v[56:57], v[60:61] op_sel_hi:[0,1]
	v_pk_mul_f32 v[62:63], v[56:57], v[62:63] op_sel_hi:[0,1]
	v_cvt_pk_bf16_f32 v208, v60, v61
	v_cvt_pk_bf16_f32 v209, v62, v63
	v_pk_mul_f32 v[64:65], v[56:57], v[64:65] op_sel_hi:[0,1]
	v_pk_mul_f32 v[66:67], v[56:57], v[66:67] op_sel_hi:[0,1]
	v_cvt_pk_bf16_f32 v210, v64, v65
	v_cvt_pk_bf16_f32 v211, v66, v67
	s_nop 1
	v_permlane16_swap_b32_e32 v208, v210
	v_permlane16_swap_b32_e32 v209, v211
	global_store_dwordx4 v[58:59], v[208:211], off
	v_pk_mul_f32 v[72:73], v[56:57], v[72:73] op_sel_hi:[0,1]
	v_pk_mul_f32 v[74:75], v[56:57], v[74:75] op_sel_hi:[0,1]
	v_cvt_pk_bf16_f32 v212, v72, v73
	v_cvt_pk_bf16_f32 v213, v74, v75
	v_pk_mul_f32 v[76:77], v[56:57], v[76:77] op_sel_hi:[0,1]
	v_pk_mul_f32 v[78:79], v[56:57], v[78:79] op_sel_hi:[0,1]
	v_cvt_pk_bf16_f32 v214, v76, v77
	v_cvt_pk_bf16_f32 v215, v78, v79
	s_nop 1
	v_permlane16_swap_b32_e32 v212, v214
	v_permlane16_swap_b32_e32 v213, v215
	global_store_dwordx4 v[58:59], v[212:215], off offset:64
	v_pk_mul_f32 v[134:135], v[56:57], v[134:135] op_sel_hi:[0,1]
	v_pk_mul_f32 v[136:137], v[56:57], v[136:137] op_sel_hi:[0,1]
	v_cvt_pk_bf16_f32 v216, v134, v135
	v_cvt_pk_bf16_f32 v217, v136, v137
	v_pk_mul_f32 v[138:139], v[56:57], v[138:139] op_sel_hi:[0,1]
	v_pk_mul_f32 v[140:141], v[56:57], v[140:141] op_sel_hi:[0,1]
	v_cvt_pk_bf16_f32 v218, v138, v139
	v_cvt_pk_bf16_f32 v219, v140, v141
	s_nop 1
	v_permlane16_swap_b32_e32 v216, v218
	v_permlane16_swap_b32_e32 v217, v219
	global_store_dwordx4 v[58:59], v[216:219], off offset:128
	v_pk_mul_f32 v[142:143], v[56:57], v[142:143] op_sel_hi:[0,1]
	v_pk_mul_f32 v[144:145], v[56:57], v[144:145] op_sel_hi:[0,1]
	v_cvt_pk_bf16_f32 v220, v142, v143
	v_cvt_pk_bf16_f32 v221, v144, v145
	v_pk_mul_f32 v[48:49], v[56:57], v[48:49] op_sel_hi:[0,1]
	v_pk_mul_f32 v[50:51], v[56:57], v[50:51] op_sel_hi:[0,1]
	v_cvt_pk_bf16_f32 v222, v48, v49
	v_cvt_pk_bf16_f32 v223, v50, v51
	s_nop 1
	v_permlane16_swap_b32_e32 v220, v222
	v_permlane16_swap_b32_e32 v221, v223
	global_store_dwordx4 v[58:59], v[220:223], off offset:192
	s_and_saveexec_b64 s[60:61], s[6:7]
	s_cbranch_execz .LBB0_146
	v_log_f32_e32 v48, v54
	s_ashr_i32 s11, s10, 31
	s_lshl_b64 s[10:11], s[10:11], 20
	s_add_u32 s10, s0, s10
	v_add_f32_e32 v50, v68, v48
	s_addc_u32 s11, s1, s11
	v_lshlrev_b64 v[48:49], 5, v[52:53]
	v_lshl_add_u64 v[48:49], s[10:11], 0, v[48:49]
	s_lshl_b32 s8, s76, 2
	v_lshl_add_u64 v[48:49], v[48:49], 0, s[8:9]
	global_store_dword v[48:49], v50, off
	s_branch .LBB0_146
